# code placement (9.3): the ten 2048-byte 8-phase K-loop heads aligned to 64 bytes (.p2align 6), on top of the best cache-policy version
# baseline (speedup 1.0000x reference)
; template <int KK, class Epi, class Sched, bool ALIGN_EPI = true>
; __device__ __forceinline__ void gemm_phase(LAS unsigned char* lds, const bf16* gA, const bf16* gBt, const Sched& S, const Epi& E, const int wid) {
;     ...
;         const bool has_next = S.next(ui + 1, nxt);
;         const char* nA = has_next ? (const char*)gA + (size_t)nxt.pm * tstep : cA; const char* nB = has_next ? (const char*)gBt + (size_t)nxt.pn * tstep : cB;
; #pragma unroll 1
;         for (int t = 0; t < nt; t += 2) {
;             const bool last = (t == nt - 2);
;             const char* a1 = cA + (size_t)(t + 1) * kstep;
;             const char* a2 = last ? nA : cA + (size_t)(t + 2) * kstep; const char* b2 = last ? nB : cB + (size_t)(t + 2) * kstep;
;             const char* a3 = a2 + kstep; const char* b3 = b2 + kstep;
;     ...
; #pragma unroll
;         for (int a = 0; a < 2; ++a)
; #pragma unroll
;             for (int b = 0; b < 2; ++b)
; #pragma unroll
;                 for (int m = 0; m < 4; ++m)
; #pragma unroll
;                     for (int n = 0; n < 2; ++n) acc[a][b][m][n] = (f32x4){0.f, 0.f, 0.f, 0.f};
.LBB0_154:
	s_ashr_i32 s53, s52, 31
	s_lshl_b64 s[8:9], s[52:53], 19
	s_add_u32 s90, s69, s8
	s_addc_u32 s91, s76, s9
	s_and_b64 s[8:9], s[88:89], exec
	s_cselect_b32 s10, s91, s7
	s_cselect_b32 s11, s90, s6
	s_ashr_i32 s87, s86, 31
	s_lshl_b64 s[8:9], s[86:87], 19
	s_add_u32 s92, s74, s8
	s_addc_u32 s93, s75, s9
	s_and_b64 s[8:9], s[88:89], exec
	s_cselect_b32 s13, s93, s5
	s_cselect_b32 s14, s92, s4
	s_add_u32 s15, s4, 0x100
	s_addc_u32 s30, s5, 0
	s_add_u32 s4, s6, 0x40080
	v_mov_b32_e32 v0, 0
	s_addc_u32 s5, s7, 0
	s_mov_b32 s31, -2
	v_mov_b32_e32 v1, v0
	v_mov_b32_e32 v2, v0
	v_mov_b32_e32 v3, v0
	v_mov_b32_e32 v4, v0
	v_mov_b32_e32 v5, v0
	v_mov_b32_e32 v6, v0
	v_mov_b32_e32 v7, v0
	v_mov_b32_e32 v16, v0
	v_mov_b32_e32 v17, v0
	v_mov_b32_e32 v18, v0
	v_mov_b32_e32 v19, v0
	v_mov_b32_e32 v20, v0
	v_mov_b32_e32 v21, v0
	v_mov_b32_e32 v22, v0
	v_mov_b32_e32 v23, v0
	v_mov_b32_e32 v32, v0
	v_mov_b32_e32 v33, v0
	v_mov_b32_e32 v34, v0
	v_mov_b32_e32 v35, v0
	v_mov_b32_e32 v36, v0
	v_mov_b32_e32 v37, v0
	v_mov_b32_e32 v38, v0
	v_mov_b32_e32 v39, v0
	v_mov_b32_e32 v48, v0
	v_mov_b32_e32 v49, v0
	v_mov_b32_e32 v50, v0
	v_mov_b32_e32 v51, v0
	v_mov_b32_e32 v52, v0
	v_mov_b32_e32 v53, v0
	v_mov_b32_e32 v54, v0
	v_mov_b32_e32 v55, v0
	v_mov_b32_e32 v8, v0
	v_mov_b32_e32 v9, v0
	v_mov_b32_e32 v10, v0
	v_mov_b32_e32 v11, v0
	v_mov_b32_e32 v12, v0
	v_mov_b32_e32 v13, v0
	s_waitcnt lgkmcnt(0)
	v_mov_b32_e32 v14, v0
	v_mov_b32_e32 v15, v0
	v_mov_b32_e32 v24, v0
	v_mov_b32_e32 v25, v0
	v_mov_b32_e32 v26, v0
	v_mov_b32_e32 v27, v0
	v_mov_b32_e32 v28, v0
	v_mov_b32_e32 v29, v0
	v_mov_b32_e32 v30, v0
	v_mov_b32_e32 v31, v0
	v_mov_b32_e32 v40, v0
	v_mov_b32_e32 v41, v0
	v_mov_b32_e32 v42, v0
	v_mov_b32_e32 v43, v0
	v_mov_b32_e32 v44, v0
	v_mov_b32_e32 v45, v0
	v_mov_b32_e32 v46, v0
	v_mov_b32_e32 v47, v0
	v_mov_b32_e32 v56, v0
	v_mov_b32_e32 v57, v0
	v_mov_b32_e32 v58, v0
	v_mov_b32_e32 v59, v0
	v_mov_b32_e32 v60, v0
	v_mov_b32_e32 v61, v0
	v_mov_b32_e32 v62, v0
	v_mov_b32_e32 v63, v0
	v_mov_b32_e32 v64, v0
	v_mov_b32_e32 v65, v0
	v_mov_b32_e32 v66, v0
	v_mov_b32_e32 v67, v0
	v_mov_b32_e32 v68, v0
	v_mov_b32_e32 v69, v0
	v_mov_b32_e32 v70, v0
	v_mov_b32_e32 v71, v0
	v_mov_b32_e32 v80, v0
	v_mov_b32_e32 v81, v0
	v_mov_b32_e32 v82, v0
	v_mov_b32_e32 v83, v0
	v_mov_b32_e32 v84, v0
	v_mov_b32_e32 v85, v0
	v_mov_b32_e32 v86, v0
	v_mov_b32_e32 v87, v0
	v_mov_b32_e32 v96, v0
	v_mov_b32_e32 v97, v0
	v_mov_b32_e32 v98, v0
	v_mov_b32_e32 v99, v0
	v_mov_b32_e32 v100, v0
	v_mov_b32_e32 v101, v0
	v_mov_b32_e32 v102, v0
	v_mov_b32_e32 v103, v0
	v_mov_b32_e32 v112, v0
	v_mov_b32_e32 v113, v0
	v_mov_b32_e32 v114, v0
	v_mov_b32_e32 v115, v0
	v_mov_b32_e32 v116, v0
	v_mov_b32_e32 v117, v0
	v_mov_b32_e32 v118, v0
	v_mov_b32_e32 v119, v0
	v_mov_b32_e32 v72, v0
	v_mov_b32_e32 v73, v0
	v_mov_b32_e32 v74, v0
	v_mov_b32_e32 v75, v0
	v_mov_b32_e32 v76, v0
	v_mov_b32_e32 v77, v0
	v_mov_b32_e32 v78, v0
	v_mov_b32_e32 v79, v0
	v_mov_b32_e32 v88, v0
	v_mov_b32_e32 v89, v0
	v_mov_b32_e32 v90, v0
	v_mov_b32_e32 v91, v0
	v_mov_b32_e32 v92, v0
	v_mov_b32_e32 v93, v0
	v_mov_b32_e32 v94, v0
	v_mov_b32_e32 v95, v0
	v_mov_b32_e32 v104, v0
	v_mov_b32_e32 v105, v0
	v_mov_b32_e32 v106, v0
	v_mov_b32_e32 v107, v0
	v_mov_b32_e32 v108, v0
	v_mov_b32_e32 v109, v0
	v_mov_b32_e32 v110, v0
	v_mov_b32_e32 v111, v0
	v_mov_b32_e32 v120, v0
	v_mov_b32_e32 v121, v0
	v_mov_b32_e32 v122, v0
	v_mov_b32_e32 v123, v0
	v_mov_b32_e32 v124, v0
	v_mov_b32_e32 v125, v0
	v_mov_b32_e32 v126, v0
	v_mov_b32_e32 v127, v0
	.p2align	6

; template <int KK, class Epi, class Sched, bool ALIGN_EPI = true>
; __device__ __forceinline__ void gemm_phase(LAS unsigned char* lds, const bf16* gA, const bf16* gBt, const Sched& S, const Epi& E, const int wid) {
;     ...
;         const bool has_next = S.next(ui + 1, nxt);
;         const char* nA = has_next ? (const char*)gA + (size_t)nxt.pm * tstep : cA; const char* nB = has_next ? (const char*)gBt + (size_t)nxt.pn * tstep : cB;
; #pragma unroll 1
;         for (int t = 0; t < nt; t += 2) {
;             const bool last = (t == nt - 2);
;             const char* a1 = cA + (size_t)(t + 1) * kstep;
;             const char* a2 = last ? nA : cA + (size_t)(t + 2) * kstep; const char* b2 = last ? nB : cB + (size_t)(t + 2) * kstep;
;             const char* a3 = a2 + kstep; const char* b3 = b2 + kstep;
;     ...
; #pragma unroll
;         for (int a = 0; a < 2; ++a)
; #pragma unroll
;             for (int b = 0; b < 2; ++b)
; #pragma unroll
;                 for (int m = 0; m < 4; ++m)
; #pragma unroll
;                     for (int n = 0; n < 2; ++n) acc[a][b][m][n] = (f32x4){0.f, 0.f, 0.f, 0.f};
.LBB0_455:
	s_ashr_i32 s15, s14, 31
	s_lshl_b64 s[36:37], s[14:15], 19
	s_add_u32 s52, s5, s36
	s_addc_u32 s53, s84, s37
	s_and_b64 s[36:37], s[42:43], exec
	s_cselect_b32 s15, s53, s59
	s_cselect_b32 s36, s52, s58
	s_ashr_i32 s31, s30, 31
	s_lshl_b64 s[38:39], s[30:31], 19
	s_add_u32 s54, s6, s38
	s_addc_u32 s55, s7, s39
	s_and_b64 s[38:39], s[42:43], exec
	s_cselect_b32 s31, s55, s57
	s_cselect_b32 s37, s54, s56
	s_add_u32 s38, s56, 0x100
	s_addc_u32 s39, s57, 0
	s_add_u32 s56, s58, 0x40080
	v_mov_b32_e32 v0, 0
	s_addc_u32 s57, s59, 0
	s_mov_b32 s48, -2
	s_waitcnt lgkmcnt(0)
	v_mov_b32_e32 v1, v0
	v_mov_b32_e32 v2, v0
	v_mov_b32_e32 v3, v0
	v_mov_b32_e32 v4, v0
	v_mov_b32_e32 v5, v0
	v_mov_b32_e32 v6, v0
	v_mov_b32_e32 v7, v0
	v_mov_b32_e32 v16, v0
	v_mov_b32_e32 v17, v0
	v_mov_b32_e32 v18, v0
	v_mov_b32_e32 v19, v0
	v_mov_b32_e32 v20, v0
	v_mov_b32_e32 v21, v0
	v_mov_b32_e32 v22, v0
	v_mov_b32_e32 v23, v0
	v_mov_b32_e32 v32, v0
	v_mov_b32_e32 v33, v0
	v_mov_b32_e32 v34, v0
	v_mov_b32_e32 v35, v0
	v_mov_b32_e32 v36, v0
	v_mov_b32_e32 v37, v0
	v_mov_b32_e32 v38, v0
	v_mov_b32_e32 v39, v0
	v_mov_b32_e32 v48, v0
	v_mov_b32_e32 v49, v0
	v_mov_b32_e32 v50, v0
	v_mov_b32_e32 v51, v0
	v_mov_b32_e32 v52, v0
	v_mov_b32_e32 v53, v0
	v_mov_b32_e32 v54, v0
	v_mov_b32_e32 v55, v0
	v_mov_b32_e32 v8, v0
	v_mov_b32_e32 v9, v0
	v_mov_b32_e32 v10, v0
	v_mov_b32_e32 v11, v0
	v_mov_b32_e32 v12, v0
	v_mov_b32_e32 v13, v0
	v_mov_b32_e32 v14, v0
	v_mov_b32_e32 v15, v0
	v_mov_b32_e32 v24, v0
	v_mov_b32_e32 v25, v0
	v_mov_b32_e32 v26, v0
	v_mov_b32_e32 v27, v0
	v_mov_b32_e32 v28, v0
	v_mov_b32_e32 v29, v0
	v_mov_b32_e32 v30, v0
	v_mov_b32_e32 v31, v0
	v_mov_b32_e32 v40, v0
	v_mov_b32_e32 v41, v0
	v_mov_b32_e32 v42, v0
	v_mov_b32_e32 v43, v0
	v_mov_b32_e32 v44, v0
	v_mov_b32_e32 v45, v0
	v_mov_b32_e32 v46, v0
	v_mov_b32_e32 v47, v0
	v_mov_b32_e32 v56, v0
	v_mov_b32_e32 v57, v0
	v_mov_b32_e32 v58, v0
	v_mov_b32_e32 v59, v0
	v_mov_b32_e32 v60, v0
	v_mov_b32_e32 v61, v0
	v_mov_b32_e32 v62, v0
	v_mov_b32_e32 v63, v0
	v_mov_b32_e32 v64, v0
	v_mov_b32_e32 v65, v0
	v_mov_b32_e32 v66, v0
	v_mov_b32_e32 v67, v0
	v_mov_b32_e32 v68, v0
	v_mov_b32_e32 v69, v0
	v_mov_b32_e32 v70, v0
	v_mov_b32_e32 v71, v0
	v_mov_b32_e32 v80, v0
	v_mov_b32_e32 v81, v0
	v_mov_b32_e32 v82, v0
	v_mov_b32_e32 v83, v0
	v_mov_b32_e32 v84, v0
	v_mov_b32_e32 v85, v0
	v_mov_b32_e32 v86, v0
	v_mov_b32_e32 v87, v0
	v_mov_b32_e32 v96, v0
	v_mov_b32_e32 v97, v0
	v_mov_b32_e32 v98, v0
	v_mov_b32_e32 v99, v0
	v_mov_b32_e32 v100, v0
	v_mov_b32_e32 v101, v0
	v_mov_b32_e32 v102, v0
	v_mov_b32_e32 v103, v0
	v_mov_b32_e32 v112, v0
	v_mov_b32_e32 v113, v0
	v_mov_b32_e32 v114, v0
	v_mov_b32_e32 v115, v0
	v_mov_b32_e32 v116, v0
	v_mov_b32_e32 v117, v0
	v_mov_b32_e32 v118, v0
	v_mov_b32_e32 v119, v0
	v_mov_b32_e32 v72, v0
	v_mov_b32_e32 v73, v0
	v_mov_b32_e32 v74, v0
	v_mov_b32_e32 v75, v0
	v_mov_b32_e32 v76, v0
	v_mov_b32_e32 v77, v0
	v_mov_b32_e32 v78, v0
	v_mov_b32_e32 v79, v0
	v_mov_b32_e32 v88, v0
	v_mov_b32_e32 v89, v0
	v_mov_b32_e32 v90, v0
	v_mov_b32_e32 v91, v0
	v_mov_b32_e32 v92, v0
	v_mov_b32_e32 v93, v0
	v_mov_b32_e32 v94, v0
	v_mov_b32_e32 v95, v0
	v_mov_b32_e32 v104, v0
	v_mov_b32_e32 v105, v0
	v_mov_b32_e32 v106, v0
	v_mov_b32_e32 v107, v0
	v_mov_b32_e32 v108, v0
	v_mov_b32_e32 v109, v0
	v_mov_b32_e32 v110, v0
	v_mov_b32_e32 v111, v0
	v_mov_b32_e32 v120, v0
	v_mov_b32_e32 v121, v0
	v_mov_b32_e32 v122, v0
	v_mov_b32_e32 v123, v0
	v_mov_b32_e32 v124, v0
	v_mov_b32_e32 v125, v0
	v_mov_b32_e32 v126, v0
	v_mov_b32_e32 v127, v0
	.p2align	6

; template <int KK, class Epi, class Sched, bool ALIGN_EPI = true>
; __device__ __forceinline__ void gemm_phase(LAS unsigned char* lds, const bf16* gA, const bf16* gBt, const Sched& S, const Epi& E, const int wid) {
;     ...
;         const bool has_next = S.next(ui + 1, nxt);
;         const char* nA = has_next ? (const char*)gA + (size_t)nxt.pm * tstep : cA; const char* nB = has_next ? (const char*)gBt + (size_t)nxt.pn * tstep : cB;
; #pragma unroll 1
;         for (int t = 0; t < nt; t += 2) {
;             const bool last = (t == nt - 2);
;             const char* a1 = cA + (size_t)(t + 1) * kstep;
;             const char* a2 = last ? nA : cA + (size_t)(t + 2) * kstep; const char* b2 = last ? nB : cB + (size_t)(t + 2) * kstep;
;             const char* a3 = a2 + kstep; const char* b3 = b2 + kstep;
;     ...
; #pragma unroll
;         for (int a = 0; a < 2; ++a)
; #pragma unroll
;             for (int b = 0; b < 2; ++b)
; #pragma unroll
;                 for (int m = 0; m < 4; ++m)
; #pragma unroll
;                     for (int n = 0; n < 2; ++n) acc[a][b][m][n] = (f32x4){0.f, 0.f, 0.f, 0.f};
.LBB0_608:
	s_ashr_i32 s15, s14, 31
	s_lshl_b64 s[36:37], s[14:15], 19
	s_add_u32 s52, s9, s36
	s_addc_u32 s53, s5, s37
	s_and_b64 s[36:37], s[42:43], exec
	s_cselect_b32 s15, s53, s77
	s_cselect_b32 s36, s52, s76
	s_ashr_i32 s31, s30, 31
	s_lshl_b64 s[38:39], s[30:31], 19
	s_add_u32 s54, s2, s38
	s_addc_u32 s55, s3, s39
	s_and_b64 s[38:39], s[42:43], exec
	s_cselect_b32 s31, s55, s67
	s_cselect_b32 s37, s54, s66
	s_add_u32 s38, s66, 0x100
	s_addc_u32 s39, s67, 0
	s_add_u32 s66, s76, 0x40080
	v_mov_b32_e32 v0, 0
	s_addc_u32 s67, s77, 0
	s_mov_b32 s48, -2
	v_mov_b32_e32 v1, v0
	v_mov_b32_e32 v2, v0
	v_mov_b32_e32 v3, v0
	v_mov_b32_e32 v8, v0
	v_mov_b32_e32 v9, v0
	v_mov_b32_e32 v10, v0
	v_mov_b32_e32 v11, v0
	v_mov_b32_e32 v16, v0
	v_mov_b32_e32 v17, v0
	v_mov_b32_e32 v18, v0
	v_mov_b32_e32 v19, v0
	v_mov_b32_e32 v24, v0
	v_mov_b32_e32 v25, v0
	v_mov_b32_e32 v26, v0
	v_mov_b32_e32 v27, v0
	v_mov_b32_e32 v32, v0
	v_mov_b32_e32 v33, v0
	v_mov_b32_e32 v34, v0
	v_mov_b32_e32 v35, v0
	v_mov_b32_e32 v40, v0
	v_mov_b32_e32 v41, v0
	v_mov_b32_e32 v42, v0
	v_mov_b32_e32 v43, v0
	v_mov_b32_e32 v48, v0
	v_mov_b32_e32 v49, v0
	v_mov_b32_e32 v50, v0
	v_mov_b32_e32 v51, v0
	v_mov_b32_e32 v56, v0
	v_mov_b32_e32 v57, v0
	v_mov_b32_e32 v58, v0
	v_mov_b32_e32 v59, v0
	v_mov_b32_e32 v4, v0
	v_mov_b32_e32 v5, v0
	v_mov_b32_e32 v6, v0
	v_mov_b32_e32 v7, v0
	v_mov_b32_e32 v12, v0
	v_mov_b32_e32 v13, v0
	v_mov_b32_e32 v14, v0
	v_mov_b32_e32 v15, v0
	v_mov_b32_e32 v20, v0
	v_mov_b32_e32 v21, v0
	v_mov_b32_e32 v22, v0
	v_mov_b32_e32 v23, v0
	v_mov_b32_e32 v28, v0
	v_mov_b32_e32 v29, v0
	v_mov_b32_e32 v30, v0
	v_mov_b32_e32 v31, v0
	v_mov_b32_e32 v36, v0
	v_mov_b32_e32 v37, v0
	v_mov_b32_e32 v38, v0
	v_mov_b32_e32 v39, v0
	v_mov_b32_e32 v44, v0
	v_mov_b32_e32 v45, v0
	v_mov_b32_e32 v46, v0
	v_mov_b32_e32 v47, v0
	v_mov_b32_e32 v52, v0
	v_mov_b32_e32 v53, v0
	v_mov_b32_e32 v54, v0
	v_mov_b32_e32 v55, v0
	v_mov_b32_e32 v60, v0
	v_mov_b32_e32 v61, v0
	v_mov_b32_e32 v62, v0
	v_mov_b32_e32 v63, v0
	v_mov_b32_e32 v64, v0
	v_mov_b32_e32 v65, v0
	v_mov_b32_e32 v66, v0
	v_mov_b32_e32 v67, v0
	v_mov_b32_e32 v72, v0
	v_mov_b32_e32 v73, v0
	v_mov_b32_e32 v74, v0
	v_mov_b32_e32 v75, v0
	v_mov_b32_e32 v80, v0
	v_mov_b32_e32 v81, v0
	v_mov_b32_e32 v82, v0
	v_mov_b32_e32 v83, v0
	v_mov_b32_e32 v88, v0
	v_mov_b32_e32 v89, v0
	v_mov_b32_e32 v90, v0
	v_mov_b32_e32 v91, v0
	v_mov_b32_e32 v96, v0
	v_mov_b32_e32 v97, v0
	v_mov_b32_e32 v98, v0
	v_mov_b32_e32 v99, v0
	v_mov_b32_e32 v104, v0
	v_mov_b32_e32 v105, v0
	v_mov_b32_e32 v106, v0
	v_mov_b32_e32 v107, v0
	v_mov_b32_e32 v112, v0
	v_mov_b32_e32 v113, v0
	v_mov_b32_e32 v114, v0
	v_mov_b32_e32 v115, v0
	v_mov_b32_e32 v120, v0
	v_mov_b32_e32 v121, v0
	v_mov_b32_e32 v122, v0
	v_mov_b32_e32 v123, v0
	v_mov_b32_e32 v68, v0
	v_mov_b32_e32 v69, v0
	v_mov_b32_e32 v70, v0
	v_mov_b32_e32 v71, v0
	v_mov_b32_e32 v76, v0
	v_mov_b32_e32 v77, v0
	v_mov_b32_e32 v78, v0
	v_mov_b32_e32 v79, v0
	v_mov_b32_e32 v84, v0
	v_mov_b32_e32 v85, v0
	v_mov_b32_e32 v86, v0
	v_mov_b32_e32 v87, v0
	v_mov_b32_e32 v92, v0
	v_mov_b32_e32 v93, v0
	v_mov_b32_e32 v94, v0
	v_mov_b32_e32 v95, v0
	v_mov_b32_e32 v100, v0
	v_mov_b32_e32 v101, v0
	v_mov_b32_e32 v102, v0
	v_mov_b32_e32 v103, v0
	v_mov_b32_e32 v108, v0
	v_mov_b32_e32 v109, v0
	v_mov_b32_e32 v110, v0
	v_mov_b32_e32 v111, v0
	v_mov_b32_e32 v116, v0
	v_mov_b32_e32 v117, v0
	v_mov_b32_e32 v118, v0
	v_mov_b32_e32 v119, v0
	v_mov_b32_e32 v124, v0
	v_mov_b32_e32 v125, v0
	v_mov_b32_e32 v126, v0
	v_mov_b32_e32 v127, v0
	.p2align	6

; template <int KK, class Epi, class Sched, bool ALIGN_EPI = true>
; __device__ __forceinline__ void gemm_phase(LAS unsigned char* lds, const bf16* gA, const bf16* gBt, const Sched& S, const Epi& E, const int wid) {
;     ...
; #pragma unroll
;         for (int a = 0; a < 2; ++a)
; #pragma unroll
;             for (int b = 0; b < 2; ++b)
; #pragma unroll
;                 for (int m = 0; m < 4; ++m)
; #pragma unroll
;                     for (int n = 0; n < 2; ++n) acc[a][b][m][n] = (f32x4){0.f, 0.f, 0.f, 0.f};
.Lp5a_cnt:
	v_mov_b32_e32 v1, v0
	v_mov_b32_e32 v2, v0
	v_mov_b32_e32 v3, v0
	v_mov_b32_e32 v4, v0
	v_mov_b32_e32 v5, v0
	v_mov_b32_e32 v6, v0
	v_mov_b32_e32 v7, v0
	v_mov_b32_e32 v12, v0
	v_mov_b32_e32 v13, v0
	v_mov_b32_e32 v14, v0
	v_mov_b32_e32 v15, v0
	v_mov_b32_e32 v20, v0
	v_mov_b32_e32 v21, v0
	v_mov_b32_e32 v22, v0
	v_mov_b32_e32 v23, v0
	v_mov_b32_e32 v28, v0
	v_mov_b32_e32 v29, v0
	v_mov_b32_e32 v30, v0
	v_mov_b32_e32 v31, v0
	v_mov_b32_e32 v36, v0
	v_mov_b32_e32 v37, v0
	v_mov_b32_e32 v38, v0
	v_mov_b32_e32 v39, v0
	v_mov_b32_e32 v44, v0
	v_mov_b32_e32 v45, v0
	v_mov_b32_e32 v46, v0
	v_mov_b32_e32 v47, v0
	v_mov_b32_e32 v52, v0
	v_mov_b32_e32 v53, v0
	v_mov_b32_e32 v54, v0
	v_mov_b32_e32 v55, v0
	v_mov_b32_e32 v8, v0
	v_mov_b32_e32 v9, v0
	v_mov_b32_e32 v10, v0
	v_mov_b32_e32 v11, v0
	v_mov_b32_e32 v16, v0
	v_mov_b32_e32 v17, v0
	v_mov_b32_e32 v18, v0
	v_mov_b32_e32 v19, v0
	v_mov_b32_e32 v24, v0
	v_mov_b32_e32 v25, v0
	v_mov_b32_e32 v26, v0
	v_mov_b32_e32 v27, v0
	v_mov_b32_e32 v32, v0
	v_mov_b32_e32 v33, v0
	v_mov_b32_e32 v34, v0
	v_mov_b32_e32 v35, v0
	v_mov_b32_e32 v40, v0
	v_mov_b32_e32 v41, v0
	v_mov_b32_e32 v42, v0
	v_mov_b32_e32 v43, v0
	v_mov_b32_e32 v48, v0
	v_mov_b32_e32 v49, v0
	v_mov_b32_e32 v50, v0
	v_mov_b32_e32 v51, v0
	v_mov_b32_e32 v56, v0
	v_mov_b32_e32 v57, v0
	v_mov_b32_e32 v58, v0
	v_mov_b32_e32 v59, v0
	v_mov_b32_e32 v60, v0
	v_mov_b32_e32 v61, v0
	v_mov_b32_e32 v62, v0
	v_mov_b32_e32 v63, v0
	v_mov_b32_e32 v64, v0
	v_mov_b32_e32 v65, v0
	v_mov_b32_e32 v66, v0
	v_mov_b32_e32 v67, v0
	v_mov_b32_e32 v68, v0
	v_mov_b32_e32 v69, v0
	v_mov_b32_e32 v70, v0
	v_mov_b32_e32 v71, v0
	v_mov_b32_e32 v76, v0
	v_mov_b32_e32 v77, v0
	v_mov_b32_e32 v78, v0
	v_mov_b32_e32 v79, v0
	v_mov_b32_e32 v84, v0
	v_mov_b32_e32 v85, v0
	v_mov_b32_e32 v86, v0
	v_mov_b32_e32 v87, v0
	v_mov_b32_e32 v92, v0
	v_mov_b32_e32 v93, v0
	v_mov_b32_e32 v94, v0
	v_mov_b32_e32 v95, v0
	v_mov_b32_e32 v100, v0
	v_mov_b32_e32 v101, v0
	v_mov_b32_e32 v102, v0
	v_mov_b32_e32 v103, v0
	v_mov_b32_e32 v108, v0
	v_mov_b32_e32 v109, v0
	v_mov_b32_e32 v110, v0
	v_mov_b32_e32 v111, v0
	v_mov_b32_e32 v116, v0
	v_mov_b32_e32 v117, v0
	v_mov_b32_e32 v118, v0
	v_mov_b32_e32 v119, v0
	v_mov_b32_e32 v72, v0
	v_mov_b32_e32 v73, v0
	v_mov_b32_e32 v74, v0
	v_mov_b32_e32 v75, v0
	v_mov_b32_e32 v80, v0
	v_mov_b32_e32 v81, v0
	v_mov_b32_e32 v82, v0
	v_mov_b32_e32 v83, v0
	v_mov_b32_e32 v88, v0
	v_mov_b32_e32 v89, v0
	v_mov_b32_e32 v90, v0
	v_mov_b32_e32 v91, v0
	v_mov_b32_e32 v96, v0
	v_mov_b32_e32 v97, v0
	v_mov_b32_e32 v98, v0
	v_mov_b32_e32 v99, v0
	v_mov_b32_e32 v104, v0
	v_mov_b32_e32 v105, v0
	v_mov_b32_e32 v106, v0
	v_mov_b32_e32 v107, v0
	v_mov_b32_e32 v112, v0
	v_mov_b32_e32 v113, v0
	v_mov_b32_e32 v114, v0
	v_mov_b32_e32 v115, v0
	v_mov_b32_e32 v120, v0
	v_mov_b32_e32 v121, v0
	v_mov_b32_e32 v122, v0
	v_mov_b32_e32 v123, v0
	v_mov_b32_e32 v124, v0
	v_mov_b32_e32 v125, v0
	v_mov_b32_e32 v126, v0
	v_mov_b32_e32 v127, v0
	.p2align	6

; template <int KK, class Epi, class Sched, bool ALIGN_EPI = true>
; __device__ __forceinline__ void gemm_phase(LAS unsigned char* lds, const bf16* gA, const bf16* gBt, const Sched& S, const Epi& E, const int wid) {
;     ...
;         const bool has_next = S.next(ui + 1, nxt);
;         const char* nA = has_next ? (const char*)gA + (size_t)nxt.pm * tstep : cA; const char* nB = has_next ? (const char*)gBt + (size_t)nxt.pn * tstep : cB;
; #pragma unroll 1
;         for (int t = 0; t < nt; t += 2) {
;             const bool last = (t == nt - 2);
;             const char* a1 = cA + (size_t)(t + 1) * kstep;
;             const char* a2 = last ? nA : cA + (size_t)(t + 2) * kstep; const char* b2 = last ? nB : cB + (size_t)(t + 2) * kstep;
;             const char* a3 = a2 + kstep; const char* b3 = b2 + kstep;
;     ...
; #pragma unroll
;         for (int a = 0; a < 2; ++a)
; #pragma unroll
;             for (int b = 0; b < 2; ++b)
; #pragma unroll
;                 for (int m = 0; m < 4; ++m)
; #pragma unroll
;                     for (int n = 0; n < 2; ++n) acc[a][b][m][n] = (f32x4){0.f, 0.f, 0.f, 0.f};
.LBB0_829:
	s_ashr_i32 s15, s14, 31
	s_lshl_b64 s[36:37], s[14:15], 19
	s_add_u32 s36, s9, s36
	s_addc_u32 s37, s5, s37
	s_and_b64 s[38:39], s[30:31], exec
	s_cselect_b32 s15, s37, s49
	s_cselect_b32 s51, s36, s48
	s_ashr_i32 s17, s16, 31
	s_lshl_b64 s[38:39], s[16:17], 19
	s_add_u32 s38, s2, s38
	s_addc_u32 s39, s3, s39
	s_and_b64 s[54:55], s[30:31], exec
	s_cselect_b32 s17, s39, s43
	s_cselect_b32 s62, s38, s42
	s_add_u32 s63, s42, 0x100
	s_addc_u32 s66, s43, 0
	s_add_u32 s42, s48, 0x40080
	v_mov_b32_e32 v0, 0
	s_addc_u32 s43, s49, 0
	s_mov_b32 s67, -2
	s_waitcnt lgkmcnt(0)
	v_mov_b32_e32 v1, v0
	v_mov_b32_e32 v2, v0
	v_mov_b32_e32 v3, v0
	v_mov_b32_e32 v4, v0
	v_mov_b32_e32 v5, v0
	v_mov_b32_e32 v6, v0
	v_mov_b32_e32 v7, v0
	v_mov_b32_e32 v16, v0
	v_mov_b32_e32 v17, v0
	v_mov_b32_e32 v18, v0
	v_mov_b32_e32 v19, v0
	v_mov_b32_e32 v20, v0
	v_mov_b32_e32 v21, v0
	v_mov_b32_e32 v22, v0
	v_mov_b32_e32 v23, v0
	v_mov_b32_e32 v32, v0
	v_mov_b32_e32 v33, v0
	v_mov_b32_e32 v34, v0
	v_mov_b32_e32 v35, v0
	v_mov_b32_e32 v36, v0
	v_mov_b32_e32 v37, v0
	v_mov_b32_e32 v38, v0
	v_mov_b32_e32 v39, v0
	v_mov_b32_e32 v48, v0
	v_mov_b32_e32 v49, v0
	v_mov_b32_e32 v50, v0
	v_mov_b32_e32 v51, v0
	v_mov_b32_e32 v52, v0
	v_mov_b32_e32 v53, v0
	v_mov_b32_e32 v54, v0
	v_mov_b32_e32 v55, v0
	v_mov_b32_e32 v8, v0
	v_mov_b32_e32 v9, v0
	v_mov_b32_e32 v10, v0
	v_mov_b32_e32 v11, v0
	v_mov_b32_e32 v12, v0
	v_mov_b32_e32 v13, v0
	v_mov_b32_e32 v14, v0
	v_mov_b32_e32 v15, v0
	v_mov_b32_e32 v24, v0
	v_mov_b32_e32 v25, v0
	v_mov_b32_e32 v26, v0
	v_mov_b32_e32 v27, v0
	v_mov_b32_e32 v28, v0
	v_mov_b32_e32 v29, v0
	v_mov_b32_e32 v30, v0
	v_mov_b32_e32 v31, v0
	v_mov_b32_e32 v40, v0
	v_mov_b32_e32 v41, v0
	v_mov_b32_e32 v42, v0
	v_mov_b32_e32 v43, v0
	v_mov_b32_e32 v44, v0
	v_mov_b32_e32 v45, v0
	v_mov_b32_e32 v46, v0
	v_mov_b32_e32 v47, v0
	v_mov_b32_e32 v56, v0
	v_mov_b32_e32 v57, v0
	v_mov_b32_e32 v58, v0
	v_mov_b32_e32 v59, v0
	v_mov_b32_e32 v60, v0
	v_mov_b32_e32 v61, v0
	v_mov_b32_e32 v62, v0
	v_mov_b32_e32 v63, v0
	v_mov_b32_e32 v64, v0
	v_mov_b32_e32 v65, v0
	v_mov_b32_e32 v66, v0
	v_mov_b32_e32 v67, v0
	v_mov_b32_e32 v68, v0
	v_mov_b32_e32 v69, v0
	v_mov_b32_e32 v70, v0
	v_mov_b32_e32 v71, v0
	v_mov_b32_e32 v80, v0
	v_mov_b32_e32 v81, v0
	v_mov_b32_e32 v82, v0
	v_mov_b32_e32 v83, v0
	v_mov_b32_e32 v84, v0
	v_mov_b32_e32 v85, v0
	v_mov_b32_e32 v86, v0
	v_mov_b32_e32 v87, v0
	v_mov_b32_e32 v96, v0
	v_mov_b32_e32 v97, v0
	v_mov_b32_e32 v98, v0
	v_mov_b32_e32 v99, v0
	v_mov_b32_e32 v100, v0
	v_mov_b32_e32 v101, v0
	v_mov_b32_e32 v102, v0
	v_mov_b32_e32 v103, v0
	v_mov_b32_e32 v112, v0
	v_mov_b32_e32 v113, v0
	v_mov_b32_e32 v114, v0
	v_mov_b32_e32 v115, v0
	v_mov_b32_e32 v116, v0
	v_mov_b32_e32 v117, v0
	v_mov_b32_e32 v118, v0
	v_mov_b32_e32 v119, v0
	v_mov_b32_e32 v72, v0
	v_mov_b32_e32 v73, v0
	v_mov_b32_e32 v74, v0
	v_mov_b32_e32 v75, v0
	v_mov_b32_e32 v76, v0
	v_mov_b32_e32 v77, v0
	v_mov_b32_e32 v78, v0
	v_mov_b32_e32 v79, v0
	v_mov_b32_e32 v88, v0
	v_mov_b32_e32 v89, v0
	v_mov_b32_e32 v90, v0
	v_mov_b32_e32 v91, v0
	v_mov_b32_e32 v92, v0
	v_mov_b32_e32 v93, v0
	v_mov_b32_e32 v94, v0
	v_mov_b32_e32 v95, v0
	v_mov_b32_e32 v104, v0
	v_mov_b32_e32 v105, v0
	v_mov_b32_e32 v106, v0
	v_mov_b32_e32 v107, v0
	v_mov_b32_e32 v108, v0
	v_mov_b32_e32 v109, v0
	v_mov_b32_e32 v110, v0
	v_mov_b32_e32 v111, v0
	v_mov_b32_e32 v120, v0
	v_mov_b32_e32 v121, v0
	v_mov_b32_e32 v122, v0
	v_mov_b32_e32 v123, v0
	v_mov_b32_e32 v124, v0
	v_mov_b32_e32 v125, v0
	v_mov_b32_e32 v126, v0
	v_mov_b32_e32 v127, v0
	.p2align	6

; template <int KK, class Epi, class Sched, bool ALIGN_EPI = true>
; __device__ __forceinline__ void gemm_phase(LAS unsigned char* lds, const bf16* gA, const bf16* gBt, const Sched& S, const Epi& E, const int wid) {
;     ...
;         const bool has_next = S.next(ui + 1, nxt);
;         const char* nA = has_next ? (const char*)gA + (size_t)nxt.pm * tstep : cA; const char* nB = has_next ? (const char*)gBt + (size_t)nxt.pn * tstep : cB;
; #pragma unroll 1
;         for (int t = 0; t < nt; t += 2) {
;             const bool last = (t == nt - 2);
;             const char* a1 = cA + (size_t)(t + 1) * kstep;
;             const char* a2 = last ? nA : cA + (size_t)(t + 2) * kstep; const char* b2 = last ? nB : cB + (size_t)(t + 2) * kstep;
;             const char* a3 = a2 + kstep; const char* b3 = b2 + kstep;
;     ...
; #pragma unroll
;         for (int a = 0; a < 2; ++a)
; #pragma unroll
;             for (int b = 0; b < 2; ++b)
; #pragma unroll
;                 for (int m = 0; m < 4; ++m)
; #pragma unroll
;                     for (int n = 0; n < 2; ++n) acc[a][b][m][n] = (f32x4){0.f, 0.f, 0.f, 0.f};
.LBB0_902:
	s_ashr_i32 s49, s48, 31
	s_lshl_b64 s[2:3], s[48:49], 19
	s_add_u32 s54, s86, s2
	s_addc_u32 s55, s87, s3
	s_and_b64 s[2:3], s[52:53], exec
	s_cselect_b32 s2, s55, s9
	s_cselect_b32 s3, s54, s8
	s_ashr_i32 s51, s50, 31
	s_lshl_b64 s[10:11], s[50:51], 19
	s_add_u32 s56, s65, s10
	s_addc_u32 s57, s69, s11
	s_and_b64 s[10:11], s[52:53], exec
	s_cselect_b32 s12, s57, s7
	s_cselect_b32 s13, s56, s6
	s_add_u32 s15, s6, 0x100
	s_addc_u32 s16, s7, 0
	s_add_u32 s6, s8, 0x40080
	v_mov_b32_e32 v0, 0
	s_addc_u32 s7, s9, 0
	s_mov_b32 s17, -2
	v_mov_b32_e32 v1, v0
	v_mov_b32_e32 v2, v0
	v_mov_b32_e32 v3, v0
	v_mov_b32_e32 v4, v0
	v_mov_b32_e32 v5, v0
	v_mov_b32_e32 v6, v0
	v_mov_b32_e32 v7, v0
	v_mov_b32_e32 v16, v0
	v_mov_b32_e32 v17, v0
	v_mov_b32_e32 v18, v0
	v_mov_b32_e32 v19, v0
	v_mov_b32_e32 v20, v0
	v_mov_b32_e32 v21, v0
	v_mov_b32_e32 v22, v0
	v_mov_b32_e32 v23, v0
	v_mov_b32_e32 v32, v0
	v_mov_b32_e32 v33, v0
	v_mov_b32_e32 v34, v0
	v_mov_b32_e32 v35, v0
	v_mov_b32_e32 v36, v0
	v_mov_b32_e32 v37, v0
	v_mov_b32_e32 v38, v0
	v_mov_b32_e32 v39, v0
	v_mov_b32_e32 v48, v0
	v_mov_b32_e32 v49, v0
	v_mov_b32_e32 v50, v0
	v_mov_b32_e32 v51, v0
	v_mov_b32_e32 v52, v0
	v_mov_b32_e32 v53, v0
	v_mov_b32_e32 v54, v0
	v_mov_b32_e32 v55, v0
	v_mov_b32_e32 v8, v0
	v_mov_b32_e32 v9, v0
	v_mov_b32_e32 v10, v0
	v_mov_b32_e32 v11, v0
	v_mov_b32_e32 v12, v0
	v_mov_b32_e32 v13, v0
	s_waitcnt lgkmcnt(0)
	v_mov_b32_e32 v14, v0
	v_mov_b32_e32 v15, v0
	v_mov_b32_e32 v24, v0
	v_mov_b32_e32 v25, v0
	v_mov_b32_e32 v26, v0
	v_mov_b32_e32 v27, v0
	v_mov_b32_e32 v28, v0
	v_mov_b32_e32 v29, v0
	v_mov_b32_e32 v30, v0
	v_mov_b32_e32 v31, v0
	v_mov_b32_e32 v40, v0
	v_mov_b32_e32 v41, v0
	v_mov_b32_e32 v42, v0
	v_mov_b32_e32 v43, v0
	v_mov_b32_e32 v44, v0
	v_mov_b32_e32 v45, v0
	v_mov_b32_e32 v46, v0
	v_mov_b32_e32 v47, v0
	v_mov_b32_e32 v56, v0
	v_mov_b32_e32 v57, v0
	v_mov_b32_e32 v58, v0
	v_mov_b32_e32 v59, v0
	v_mov_b32_e32 v60, v0
	v_mov_b32_e32 v61, v0
	v_mov_b32_e32 v62, v0
	v_mov_b32_e32 v63, v0
	v_mov_b32_e32 v64, v0
	v_mov_b32_e32 v65, v0
	v_mov_b32_e32 v66, v0
	v_mov_b32_e32 v67, v0
	v_mov_b32_e32 v68, v0
	v_mov_b32_e32 v69, v0
	v_mov_b32_e32 v70, v0
	v_mov_b32_e32 v71, v0
	v_mov_b32_e32 v80, v0
	v_mov_b32_e32 v81, v0
	v_mov_b32_e32 v82, v0
	v_mov_b32_e32 v83, v0
	v_mov_b32_e32 v84, v0
	v_mov_b32_e32 v85, v0
	v_mov_b32_e32 v86, v0
	v_mov_b32_e32 v87, v0
	v_mov_b32_e32 v96, v0
	v_mov_b32_e32 v97, v0
	v_mov_b32_e32 v98, v0
	v_mov_b32_e32 v99, v0
	v_mov_b32_e32 v100, v0
	v_mov_b32_e32 v101, v0
	v_mov_b32_e32 v102, v0
	v_mov_b32_e32 v103, v0
	v_mov_b32_e32 v112, v0
	v_mov_b32_e32 v113, v0
	v_mov_b32_e32 v114, v0
	v_mov_b32_e32 v115, v0
	v_mov_b32_e32 v116, v0
	v_mov_b32_e32 v117, v0
	v_mov_b32_e32 v118, v0
	v_mov_b32_e32 v119, v0
	v_mov_b32_e32 v72, v0
	v_mov_b32_e32 v73, v0
	v_mov_b32_e32 v74, v0
	v_mov_b32_e32 v75, v0
	v_mov_b32_e32 v76, v0
	v_mov_b32_e32 v77, v0
	v_mov_b32_e32 v78, v0
	v_mov_b32_e32 v79, v0
	v_mov_b32_e32 v88, v0
	v_mov_b32_e32 v89, v0
	v_mov_b32_e32 v90, v0
	v_mov_b32_e32 v91, v0
	v_mov_b32_e32 v92, v0
	v_mov_b32_e32 v93, v0
	v_mov_b32_e32 v94, v0
	v_mov_b32_e32 v95, v0
	v_mov_b32_e32 v104, v0
	v_mov_b32_e32 v105, v0
	v_mov_b32_e32 v106, v0
	v_mov_b32_e32 v107, v0
	v_mov_b32_e32 v108, v0
	v_mov_b32_e32 v109, v0
	v_mov_b32_e32 v110, v0
	v_mov_b32_e32 v111, v0
	v_mov_b32_e32 v120, v0
	v_mov_b32_e32 v121, v0
	v_mov_b32_e32 v122, v0
	v_mov_b32_e32 v123, v0
	v_mov_b32_e32 v124, v0
	v_mov_b32_e32 v125, v0
	v_mov_b32_e32 v126, v0
	v_mov_b32_e32 v127, v0
	.p2align	6

; template <int KK, class Epi, class Sched, bool ALIGN_EPI = true>
; __device__ __forceinline__ void gemm_phase(LAS unsigned char* lds, const bf16* gA, const bf16* gBt, const Sched& S, const Epi& E, const int wid) {
;     ...
;         const bool has_next = S.next(ui + 1, nxt);
;         const char* nA = has_next ? (const char*)gA + (size_t)nxt.pm * tstep : cA; const char* nB = has_next ? (const char*)gBt + (size_t)nxt.pn * tstep : cB;
; #pragma unroll 1
;         for (int t = 0; t < nt; t += 2) {
;             const bool last = (t == nt - 2);
;             const char* a1 = cA + (size_t)(t + 1) * kstep;
;             const char* a2 = last ? nA : cA + (size_t)(t + 2) * kstep; const char* b2 = last ? nB : cB + (size_t)(t + 2) * kstep;
;             const char* a3 = a2 + kstep; const char* b3 = b2 + kstep;
;     ...
; #pragma unroll
;         for (int a = 0; a < 2; ++a)
; #pragma unroll
;             for (int b = 0; b < 2; ++b)
; #pragma unroll
;                 for (int m = 0; m < 4; ++m)
; #pragma unroll
;                     for (int n = 0; n < 2; ++n) acc[a][b][m][n] = (f32x4){0.f, 0.f, 0.f, 0.f};
.LBB0_1185:
	s_ashr_i32 s15, s14, 31
	s_lshl_b64 s[26:27], s[14:15], 19
	s_add_u32 s26, s50, s26
	s_addc_u32 s27, s51, s27
	s_and_b64 s[30:31], s[24:25], exec
	s_cselect_b32 s15, s27, s45
	s_cselect_b32 s37, s26, s44
	s_ashr_i32 s17, s16, 31
	s_lshl_b64 s[30:31], s[16:17], 19
	s_add_u32 s30, s2, s30
	s_addc_u32 s31, s3, s31
	s_and_b64 s[46:47], s[24:25], exec
	s_cselect_b32 s17, s31, s43
	s_cselect_b32 s56, s30, s42
	s_add_u32 s57, s42, 0x100
	s_addc_u32 s58, s43, 0
	s_add_u32 s42, s44, 0x40080
	v_mov_b32_e32 v0, 0
	s_addc_u32 s43, s45, 0
	s_mov_b32 s59, -2
	s_waitcnt lgkmcnt(0)
	v_mov_b32_e32 v1, v0
	v_mov_b32_e32 v2, v0
	v_mov_b32_e32 v3, v0
	v_mov_b32_e32 v4, v0
	v_mov_b32_e32 v5, v0
	v_mov_b32_e32 v6, v0
	v_mov_b32_e32 v7, v0
	v_mov_b32_e32 v16, v0
	v_mov_b32_e32 v17, v0
	v_mov_b32_e32 v18, v0
	v_mov_b32_e32 v19, v0
	v_mov_b32_e32 v20, v0
	v_mov_b32_e32 v21, v0
	v_mov_b32_e32 v22, v0
	v_mov_b32_e32 v23, v0
	v_mov_b32_e32 v32, v0
	v_mov_b32_e32 v33, v0
	v_mov_b32_e32 v34, v0
	v_mov_b32_e32 v35, v0
	v_mov_b32_e32 v36, v0
	v_mov_b32_e32 v37, v0
	v_mov_b32_e32 v38, v0
	v_mov_b32_e32 v39, v0
	v_mov_b32_e32 v48, v0
	v_mov_b32_e32 v49, v0
	v_mov_b32_e32 v50, v0
	v_mov_b32_e32 v51, v0
	v_mov_b32_e32 v52, v0
	v_mov_b32_e32 v53, v0
	v_mov_b32_e32 v54, v0
	v_mov_b32_e32 v55, v0
	v_mov_b32_e32 v8, v0
	v_mov_b32_e32 v9, v0
	v_mov_b32_e32 v10, v0
	v_mov_b32_e32 v11, v0
	v_mov_b32_e32 v12, v0
	v_mov_b32_e32 v13, v0
	v_mov_b32_e32 v14, v0
	v_mov_b32_e32 v15, v0
	v_mov_b32_e32 v24, v0
	v_mov_b32_e32 v25, v0
	v_mov_b32_e32 v26, v0
	v_mov_b32_e32 v27, v0
	v_mov_b32_e32 v28, v0
	v_mov_b32_e32 v29, v0
	v_mov_b32_e32 v30, v0
	v_mov_b32_e32 v31, v0
	v_mov_b32_e32 v40, v0
	v_mov_b32_e32 v41, v0
	v_mov_b32_e32 v42, v0
	v_mov_b32_e32 v43, v0
	v_mov_b32_e32 v44, v0
	v_mov_b32_e32 v45, v0
	v_mov_b32_e32 v46, v0
	v_mov_b32_e32 v47, v0
	v_mov_b32_e32 v56, v0
	v_mov_b32_e32 v57, v0
	v_mov_b32_e32 v58, v0
	v_mov_b32_e32 v59, v0
	v_mov_b32_e32 v60, v0
	v_mov_b32_e32 v61, v0
	v_mov_b32_e32 v62, v0
	v_mov_b32_e32 v63, v0
	v_mov_b32_e32 v64, v0
	v_mov_b32_e32 v65, v0
	v_mov_b32_e32 v66, v0
	v_mov_b32_e32 v67, v0
	v_mov_b32_e32 v68, v0
	v_mov_b32_e32 v69, v0
	v_mov_b32_e32 v70, v0
	v_mov_b32_e32 v71, v0
	v_mov_b32_e32 v80, v0
	v_mov_b32_e32 v81, v0
	v_mov_b32_e32 v82, v0
	v_mov_b32_e32 v83, v0
	v_mov_b32_e32 v84, v0
	v_mov_b32_e32 v85, v0
	v_mov_b32_e32 v86, v0
	v_mov_b32_e32 v87, v0
	v_mov_b32_e32 v96, v0
	v_mov_b32_e32 v97, v0
	v_mov_b32_e32 v98, v0
	v_mov_b32_e32 v99, v0
	v_mov_b32_e32 v100, v0
	v_mov_b32_e32 v101, v0
	v_mov_b32_e32 v102, v0
	v_mov_b32_e32 v103, v0
	v_mov_b32_e32 v112, v0
	v_mov_b32_e32 v113, v0
	v_mov_b32_e32 v114, v0
	v_mov_b32_e32 v115, v0
	v_mov_b32_e32 v116, v0
	v_mov_b32_e32 v117, v0
	v_mov_b32_e32 v118, v0
	v_mov_b32_e32 v119, v0
	v_mov_b32_e32 v72, v0
	v_mov_b32_e32 v73, v0
	v_mov_b32_e32 v74, v0
	v_mov_b32_e32 v75, v0
	v_mov_b32_e32 v76, v0
	v_mov_b32_e32 v77, v0
	v_mov_b32_e32 v78, v0
	v_mov_b32_e32 v79, v0
	v_mov_b32_e32 v88, v0
	v_mov_b32_e32 v89, v0
	v_mov_b32_e32 v90, v0
	v_mov_b32_e32 v91, v0
	v_mov_b32_e32 v92, v0
	v_mov_b32_e32 v93, v0
	v_mov_b32_e32 v94, v0
	v_mov_b32_e32 v95, v0
	v_mov_b32_e32 v104, v0
	v_mov_b32_e32 v105, v0
	v_mov_b32_e32 v106, v0
	v_mov_b32_e32 v107, v0
	v_mov_b32_e32 v108, v0
	v_mov_b32_e32 v109, v0
	v_mov_b32_e32 v110, v0
	v_mov_b32_e32 v111, v0
	v_mov_b32_e32 v120, v0
	v_mov_b32_e32 v121, v0
	v_mov_b32_e32 v122, v0
	v_mov_b32_e32 v123, v0
	v_mov_b32_e32 v124, v0
	v_mov_b32_e32 v125, v0
	v_mov_b32_e32 v126, v0
	v_mov_b32_e32 v127, v0
	.p2align	6

; template <int KK, class Epi, class Sched, bool ALIGN_EPI = true>
; __device__ __forceinline__ void gemm_phase(LAS unsigned char* lds, const bf16* gA, const bf16* gBt, const Sched& S, const Epi& E, const int wid) {
;     ...
;         const bool has_next = S.next(ui + 1, nxt);
;         const char* nA = has_next ? (const char*)gA + (size_t)nxt.pm * tstep : cA; const char* nB = has_next ? (const char*)gBt + (size_t)nxt.pn * tstep : cB;
; #pragma unroll 1
;         for (int t = 0; t < nt; t += 2) {
;             const bool last = (t == nt - 2);
;             const char* a1 = cA + (size_t)(t + 1) * kstep;
;             const char* a2 = last ? nA : cA + (size_t)(t + 2) * kstep; const char* b2 = last ? nB : cB + (size_t)(t + 2) * kstep;
;             const char* a3 = a2 + kstep; const char* b3 = b2 + kstep;
;     ...
; #pragma unroll
;         for (int a = 0; a < 2; ++a)
; #pragma unroll
;             for (int b = 0; b < 2; ++b)
; #pragma unroll
;                 for (int m = 0; m < 4; ++m)
; #pragma unroll
;                     for (int n = 0; n < 2; ++n) acc[a][b][m][n] = (f32x4){0.f, 0.f, 0.f, 0.f};
.LBB0_1245:
	s_ashr_i32 s15, s14, 31
	s_lshl_b64 s[26:27], s[14:15], 19
	s_add_u32 s26, s4, s26
	s_addc_u32 s27, s56, s27
	s_and_b64 s[30:31], s[24:25], exec
	s_cselect_b32 s15, s27, s45
	s_cselect_b32 s55, s26, s44
	s_ashr_i32 s17, s16, 31
	s_lshl_b64 s[30:31], s[16:17], 19
	s_add_u32 s30, s2, s30
	s_addc_u32 s31, s3, s31
	s_and_b64 s[46:47], s[24:25], exec
	s_cselect_b32 s17, s31, s43
	s_cselect_b32 s57, s30, s42
	s_add_u32 s58, s42, 0x100
	s_addc_u32 s59, s43, 0
	s_add_u32 s42, s44, 0x40080
	v_mov_b32_e32 v0, 0
	s_addc_u32 s43, s45, 0
	s_mov_b32 s60, -2
	v_mov_b32_e32 v1, v0
	v_mov_b32_e32 v2, v0
	v_mov_b32_e32 v3, v0
	v_mov_b32_e32 v8, v0
	v_mov_b32_e32 v9, v0
	v_mov_b32_e32 v10, v0
	v_mov_b32_e32 v11, v0
	v_mov_b32_e32 v16, v0
	v_mov_b32_e32 v17, v0
	v_mov_b32_e32 v18, v0
	v_mov_b32_e32 v19, v0
	v_mov_b32_e32 v24, v0
	v_mov_b32_e32 v25, v0
	v_mov_b32_e32 v26, v0
	v_mov_b32_e32 v27, v0
	v_mov_b32_e32 v32, v0
	v_mov_b32_e32 v33, v0
	v_mov_b32_e32 v34, v0
	v_mov_b32_e32 v35, v0
	v_mov_b32_e32 v40, v0
	v_mov_b32_e32 v41, v0
	v_mov_b32_e32 v42, v0
	v_mov_b32_e32 v43, v0
	v_mov_b32_e32 v48, v0
	v_mov_b32_e32 v49, v0
	v_mov_b32_e32 v50, v0
	v_mov_b32_e32 v51, v0
	v_mov_b32_e32 v56, v0
	v_mov_b32_e32 v57, v0
	v_mov_b32_e32 v58, v0
	v_mov_b32_e32 v59, v0
	v_mov_b32_e32 v4, v0
	v_mov_b32_e32 v5, v0
	v_mov_b32_e32 v6, v0
	v_mov_b32_e32 v7, v0
	v_mov_b32_e32 v12, v0
	v_mov_b32_e32 v13, v0
	v_mov_b32_e32 v14, v0
	v_mov_b32_e32 v15, v0
	v_mov_b32_e32 v20, v0
	v_mov_b32_e32 v21, v0
	v_mov_b32_e32 v22, v0
	v_mov_b32_e32 v23, v0
	v_mov_b32_e32 v28, v0
	v_mov_b32_e32 v29, v0
	v_mov_b32_e32 v30, v0
	v_mov_b32_e32 v31, v0
	v_mov_b32_e32 v36, v0
	v_mov_b32_e32 v37, v0
	v_mov_b32_e32 v38, v0
	v_mov_b32_e32 v39, v0
	v_mov_b32_e32 v44, v0
	v_mov_b32_e32 v45, v0
	v_mov_b32_e32 v46, v0
	v_mov_b32_e32 v47, v0
	v_mov_b32_e32 v52, v0
	v_mov_b32_e32 v53, v0
	v_mov_b32_e32 v54, v0
	v_mov_b32_e32 v55, v0
	v_mov_b32_e32 v60, v0
	v_mov_b32_e32 v61, v0
	v_mov_b32_e32 v62, v0
	v_mov_b32_e32 v63, v0
	v_mov_b32_e32 v64, v0
	v_mov_b32_e32 v65, v0
	v_mov_b32_e32 v66, v0
	v_mov_b32_e32 v67, v0
	v_mov_b32_e32 v72, v0
	v_mov_b32_e32 v73, v0
	v_mov_b32_e32 v74, v0
	v_mov_b32_e32 v75, v0
	v_mov_b32_e32 v80, v0
	v_mov_b32_e32 v81, v0
	v_mov_b32_e32 v82, v0
	v_mov_b32_e32 v83, v0
	v_mov_b32_e32 v88, v0
	v_mov_b32_e32 v89, v0
	v_mov_b32_e32 v90, v0
	v_mov_b32_e32 v91, v0
	v_mov_b32_e32 v96, v0
	v_mov_b32_e32 v97, v0
	v_mov_b32_e32 v98, v0
	v_mov_b32_e32 v99, v0
	v_mov_b32_e32 v104, v0
	v_mov_b32_e32 v105, v0
	v_mov_b32_e32 v106, v0
	v_mov_b32_e32 v107, v0
	v_mov_b32_e32 v120, v0
	v_mov_b32_e32 v121, v0
	v_mov_b32_e32 v122, v0
	v_mov_b32_e32 v123, v0
	v_mov_b32_e32 v124, v0
	v_mov_b32_e32 v125, v0
	v_mov_b32_e32 v126, v0
	v_mov_b32_e32 v127, v0
	v_mov_b32_e32 v68, v0
	v_mov_b32_e32 v69, v0
	v_mov_b32_e32 v70, v0
	v_mov_b32_e32 v71, v0
	v_mov_b32_e32 v76, v0
	v_mov_b32_e32 v77, v0
	v_mov_b32_e32 v78, v0
	v_mov_b32_e32 v79, v0
	v_mov_b32_e32 v84, v0
	v_mov_b32_e32 v85, v0
	v_mov_b32_e32 v86, v0
	v_mov_b32_e32 v87, v0
	v_mov_b32_e32 v92, v0
	v_mov_b32_e32 v93, v0
	v_mov_b32_e32 v94, v0
	v_mov_b32_e32 v95, v0
	v_mov_b32_e32 v100, v0
	v_mov_b32_e32 v101, v0
	v_mov_b32_e32 v102, v0
	v_mov_b32_e32 v103, v0
	v_mov_b32_e32 v108, v0
	v_mov_b32_e32 v109, v0
	v_mov_b32_e32 v110, v0
	v_mov_b32_e32 v111, v0
	v_mov_b32_e32 v112, v0
	v_mov_b32_e32 v113, v0
	v_mov_b32_e32 v114, v0
	v_mov_b32_e32 v115, v0
	v_mov_b32_e32 v116, v0
	v_mov_b32_e32 v117, v0
	v_mov_b32_e32 v118, v0
	v_mov_b32_e32 v119, v0
	.p2align	6

; template <int KK, class Epi, class Sched, bool ALIGN_EPI = true>
; __device__ __forceinline__ void gemm_phase(LAS unsigned char* lds, const bf16* gA, const bf16* gBt, const Sched& S, const Epi& E, const int wid) {
;     ...
;         const bool has_next = S.next(ui + 1, nxt);
;         const char* nA = has_next ? (const char*)gA + (size_t)nxt.pm * tstep : cA; const char* nB = has_next ? (const char*)gBt + (size_t)nxt.pn * tstep : cB;
; #pragma unroll 1
;         for (int t = 0; t < nt; t += 2) {
;             const bool last = (t == nt - 2);
;             const char* a1 = cA + (size_t)(t + 1) * kstep;
;             const char* a2 = last ? nA : cA + (size_t)(t + 2) * kstep; const char* b2 = last ? nB : cB + (size_t)(t + 2) * kstep;
;             const char* a3 = a2 + kstep; const char* b3 = b2 + kstep;
;     ...
; #pragma unroll
;         for (int a = 0; a < 2; ++a)
; #pragma unroll
;             for (int b = 0; b < 2; ++b)
; #pragma unroll
;                 for (int m = 0; m < 4; ++m)
; #pragma unroll
;                     for (int n = 0; n < 2; ++n) acc[a][b][m][n] = (f32x4){0.f, 0.f, 0.f, 0.f};
.LBB0_1368:
	s_ashr_i32 s11, s10, 31
	s_lshl_b64 s[16:17], s[10:11], 19
	s_add_u32 s16, s4, s16
	s_addc_u32 s17, s56, s17
	s_and_b64 s[18:19], s[14:15], exec
	s_cselect_b32 s11, s17, s27
	s_cselect_b32 s31, s16, s26
	s_ashr_i32 s13, s12, 31
	s_lshl_b64 s[18:19], s[12:13], 19
	s_add_u32 s18, s3, s18
	s_addc_u32 s19, s5, s19
	s_and_b64 s[38:39], s[14:15], exec
	s_cselect_b32 s13, s19, s25
	s_cselect_b32 s50, s18, s24
	s_add_u32 s51, s24, 0x100
	s_addc_u32 s52, s25, 0
	s_add_u32 s24, s26, 0x40080
	v_mov_b32_e32 v0, 0
	s_addc_u32 s25, s27, 0
	s_mov_b32 s53, -2
	s_waitcnt lgkmcnt(0)
	v_mov_b32_e32 v1, v0
	v_mov_b32_e32 v2, v0
	v_mov_b32_e32 v3, v0
	v_mov_b32_e32 v4, v0
	v_mov_b32_e32 v5, v0
	v_mov_b32_e32 v6, v0
	v_mov_b32_e32 v7, v0
	v_mov_b32_e32 v16, v0
	v_mov_b32_e32 v17, v0
	v_mov_b32_e32 v18, v0
	v_mov_b32_e32 v19, v0
	v_mov_b32_e32 v20, v0
	v_mov_b32_e32 v21, v0
	v_mov_b32_e32 v22, v0
	v_mov_b32_e32 v23, v0
	v_mov_b32_e32 v32, v0
	v_mov_b32_e32 v33, v0
	v_mov_b32_e32 v34, v0
	v_mov_b32_e32 v35, v0
	v_mov_b32_e32 v36, v0
	v_mov_b32_e32 v37, v0
	v_mov_b32_e32 v38, v0
	v_mov_b32_e32 v39, v0
	v_mov_b32_e32 v48, v0
	v_mov_b32_e32 v49, v0
	v_mov_b32_e32 v50, v0
	v_mov_b32_e32 v51, v0
	v_mov_b32_e32 v52, v0
	v_mov_b32_e32 v53, v0
	v_mov_b32_e32 v54, v0
	v_mov_b32_e32 v55, v0
	v_mov_b32_e32 v8, v0
	v_mov_b32_e32 v9, v0
	v_mov_b32_e32 v10, v0
	v_mov_b32_e32 v11, v0
	v_mov_b32_e32 v12, v0
	v_mov_b32_e32 v13, v0
	v_mov_b32_e32 v14, v0
	v_mov_b32_e32 v15, v0
	v_mov_b32_e32 v24, v0
	v_mov_b32_e32 v25, v0
	v_mov_b32_e32 v26, v0
	v_mov_b32_e32 v27, v0
	v_mov_b32_e32 v28, v0
	v_mov_b32_e32 v29, v0
	v_mov_b32_e32 v30, v0
	v_mov_b32_e32 v31, v0
	v_mov_b32_e32 v40, v0
	v_mov_b32_e32 v41, v0
	v_mov_b32_e32 v42, v0
	v_mov_b32_e32 v43, v0
	v_mov_b32_e32 v44, v0
	v_mov_b32_e32 v45, v0
	v_mov_b32_e32 v46, v0
	v_mov_b32_e32 v47, v0
	v_mov_b32_e32 v56, v0
	v_mov_b32_e32 v57, v0
	v_mov_b32_e32 v58, v0
	v_mov_b32_e32 v59, v0
	v_mov_b32_e32 v60, v0
	v_mov_b32_e32 v61, v0
	v_mov_b32_e32 v62, v0
	v_mov_b32_e32 v63, v0
	v_mov_b32_e32 v64, v0
	v_mov_b32_e32 v65, v0
	v_mov_b32_e32 v66, v0
	v_mov_b32_e32 v67, v0
	v_mov_b32_e32 v68, v0
	v_mov_b32_e32 v69, v0
	v_mov_b32_e32 v70, v0
	v_mov_b32_e32 v71, v0
	v_mov_b32_e32 v80, v0
	v_mov_b32_e32 v81, v0
	v_mov_b32_e32 v82, v0
	v_mov_b32_e32 v83, v0
	v_mov_b32_e32 v84, v0
	v_mov_b32_e32 v85, v0
	v_mov_b32_e32 v86, v0
	v_mov_b32_e32 v87, v0
	v_mov_b32_e32 v96, v0
	v_mov_b32_e32 v97, v0
	v_mov_b32_e32 v98, v0
	v_mov_b32_e32 v99, v0
	v_mov_b32_e32 v100, v0
	v_mov_b32_e32 v101, v0
	v_mov_b32_e32 v102, v0
	v_mov_b32_e32 v103, v0
	v_mov_b32_e32 v112, v0
	v_mov_b32_e32 v113, v0
	v_mov_b32_e32 v114, v0
	v_mov_b32_e32 v115, v0
	v_mov_b32_e32 v116, v0
	v_mov_b32_e32 v117, v0
	v_mov_b32_e32 v118, v0
	v_mov_b32_e32 v119, v0
	v_mov_b32_e32 v72, v0
	v_mov_b32_e32 v73, v0
	v_mov_b32_e32 v74, v0
	v_mov_b32_e32 v75, v0
	v_mov_b32_e32 v76, v0
	v_mov_b32_e32 v77, v0
	v_mov_b32_e32 v78, v0
	v_mov_b32_e32 v79, v0
	v_mov_b32_e32 v88, v0
	v_mov_b32_e32 v89, v0
	v_mov_b32_e32 v90, v0
	v_mov_b32_e32 v91, v0
	v_mov_b32_e32 v92, v0
	v_mov_b32_e32 v93, v0
	v_mov_b32_e32 v94, v0
	v_mov_b32_e32 v95, v0
	v_mov_b32_e32 v104, v0
	v_mov_b32_e32 v105, v0
	v_mov_b32_e32 v106, v0
	v_mov_b32_e32 v107, v0
	v_mov_b32_e32 v108, v0
	v_mov_b32_e32 v109, v0
	v_mov_b32_e32 v110, v0
	v_mov_b32_e32 v111, v0
	v_mov_b32_e32 v120, v0
	v_mov_b32_e32 v121, v0
	v_mov_b32_e32 v122, v0
	v_mov_b32_e32 v123, v0
	v_mov_b32_e32 v124, v0
	v_mov_b32_e32 v125, v0
	v_mov_b32_e32 v126, v0
	v_mov_b32_e32 v127, v0
	.p2align	6
